# per-MFMA counted LDS waits in the GEMM k-loops (each MFMA waits only for its own fragments) on top of previous version
# speedup vs baseline: 1.0534x; 1.0042x over previous
; #define MFMA(a, b, c) __builtin_amdgcn_mfma_f32_32x32x16_bf16((a), (b), (c), 0, 0, 0)
; #define GEMM_ISSUE(KT, ST) do { const int k1_ = (KT) << 6; unsigned char* d_ = ldst + (ST) * STAGE; \
;         _Pragma("unroll") for (int j_ = 0; j_ < 4; ++j_) dma16(ap + (size_t)(64 * j_) * lda + k1_, d_ + j_ * 8192); \
;         _Pragma("unroll") for (int j_ = 0; j_ < NBW; ++j_) dma16(bp + bro[j_] + k1_, d_ + BOFF + j_ * 8192); } while (0)
; template <int NBW>
; DI void gemm_mainloop(f32x16 (&acc)[2][NBW], const bf16_t* A, size_t lda, int m0, const bf16_t* Bt, size_t ldb, int n0, int K, unsigned char* lds, bool pre = false, bool only_issue = false) {
;     ...
;     for (int kt = 0; kt < nk; ++kt) {
;         const unsigned char* st = lds + (kt & 1) * STAGE;
; #pragma unroll
;         for (int s = 0; s < 4; ++s) {
;             if (s == 1 && kt + 1 < nk) GEMM_ISSUE(kt + 1, (kt + 1) & 1);
;             bf16x8 a[2], b[NBW];
; #pragma unroll
;             for (int mb = 0; mb < 2; ++mb) a[mb] = *(const bf16x8*)(st + aofs + mb * 4096 + xo[s]);
; #pragma unroll
;             for (int nb = 0; nb < NBW; ++nb) b[nb] = *(const bf16x8*)(st + bofs + nb * 4096 + xo[s]);
; #pragma unroll
;             for (int mb = 0; mb < 2; ++mb)
; #pragma unroll
;                 for (int nb = 0; nb < NBW; ++nb) acc[mb][nb] = MFMA(a[mb], b[nb], acc[mb][nb]);
;         }
;         __syncthreads();
.Lp1_kloop:
	v_add_u32_e32 v252, v138, v144
	v_add_u32_e32 v253, v149, v144
	ds_read_b128 v[150:153], v252
	ds_read_b128 v[170:173], v253 offset:32768
	ds_read_b128 v[174:177], v253 offset:36864
	ds_read_b128 v[178:181], v253 offset:40960
	ds_read_b128 v[182:185], v253 offset:45056
	ds_read_b128 v[166:169], v252 offset:4096
	s_waitcnt lgkmcnt(10)
	v_mfma_f32_32x32x16_bf16 v[114:129], v[224:227], v[232:235], v[114:129]
	s_waitcnt lgkmcnt(9)
	v_mfma_f32_32x32x16_bf16 v[82:97], v[224:227], v[236:239], v[82:97]
	s_waitcnt lgkmcnt(8)
	v_mfma_f32_32x32x16_bf16 v[98:113], v[224:227], v[240:243], v[98:113]
	s_waitcnt lgkmcnt(7)
	v_mfma_f32_32x32x16_bf16 v[66:81], v[224:227], v[244:247], v[66:81]
	s_waitcnt lgkmcnt(6)
	v_mfma_f32_32x32x16_bf16 v[50:65], v[228:231], v[232:235], v[50:65]
	v_mfma_f32_32x32x16_bf16 v[18:33], v[228:231], v[236:239], v[18:33]
	v_mfma_f32_32x32x16_bf16 v[34:49], v[228:231], v[240:243], v[34:49]
	v_mfma_f32_32x32x16_bf16 v[2:17], v[228:231], v[244:247], v[2:17]
	v_add_u32_e32 v252, v138, v145
	v_add_u32_e32 v253, v149, v145
	ds_read_b128 v[224:227], v252
	ds_read_b128 v[232:235], v253 offset:32768
	ds_read_b128 v[236:239], v253 offset:36864
	ds_read_b128 v[240:243], v253 offset:40960
	ds_read_b128 v[244:247], v253 offset:45056
	ds_read_b128 v[228:231], v252 offset:4096
	s_waitcnt lgkmcnt(10)
	v_mfma_f32_32x32x16_bf16 v[114:129], v[150:153], v[170:173], v[114:129]
	s_waitcnt lgkmcnt(9)
	v_mfma_f32_32x32x16_bf16 v[82:97], v[150:153], v[174:177], v[82:97]
	s_waitcnt lgkmcnt(8)
	v_mfma_f32_32x32x16_bf16 v[98:113], v[150:153], v[178:181], v[98:113]
	s_waitcnt lgkmcnt(7)
	v_mfma_f32_32x32x16_bf16 v[66:81], v[150:153], v[182:185], v[66:81]
	s_waitcnt lgkmcnt(6)
	v_mfma_f32_32x32x16_bf16 v[50:65], v[166:169], v[170:173], v[50:65]
	v_mfma_f32_32x32x16_bf16 v[18:33], v[166:169], v[174:177], v[18:33]
	v_mfma_f32_32x32x16_bf16 v[34:49], v[166:169], v[178:181], v[34:49]
	v_mfma_f32_32x32x16_bf16 v[2:17], v[166:169], v[182:185], v[2:17]
	v_add_u32_e32 v252, v138, v146
	v_add_u32_e32 v253, v149, v146
	ds_read_b128 v[150:153], v252
	ds_read_b128 v[170:173], v253 offset:32768
	ds_read_b128 v[174:177], v253 offset:36864
	ds_read_b128 v[178:181], v253 offset:40960
	ds_read_b128 v[182:185], v253 offset:45056
	ds_read_b128 v[166:169], v252 offset:4096
	s_waitcnt lgkmcnt(10)
	v_mfma_f32_32x32x16_bf16 v[114:129], v[224:227], v[232:235], v[114:129]
	s_waitcnt lgkmcnt(9)
	v_mfma_f32_32x32x16_bf16 v[82:97], v[224:227], v[236:239], v[82:97]
	s_waitcnt lgkmcnt(8)
	v_mfma_f32_32x32x16_bf16 v[98:113], v[224:227], v[240:243], v[98:113]
	s_waitcnt lgkmcnt(7)
	v_mfma_f32_32x32x16_bf16 v[66:81], v[224:227], v[244:247], v[66:81]
	s_waitcnt lgkmcnt(6)
	v_mfma_f32_32x32x16_bf16 v[50:65], v[228:231], v[232:235], v[50:65]
	v_mfma_f32_32x32x16_bf16 v[18:33], v[228:231], v[236:239], v[18:33]
	v_mfma_f32_32x32x16_bf16 v[34:49], v[228:231], v[240:243], v[34:49]
	v_mfma_f32_32x32x16_bf16 v[2:17], v[228:231], v[244:247], v[2:17]
	v_xor_b32_e32 v138, 0x10000, v138
	v_xor_b32_e32 v149, 0x10000, v149
	s_waitcnt vmcnt(0) lgkmcnt(0)
	s_barrier
	s_cmp_eq_u32 s2, 0x800
	s_cbranch_scc1 .Lp1_klast
	v_add_u32_e32 v252, v138, v143
	v_add_u32_e32 v253, v149, v143
	ds_read_b128 v[224:227], v252
	ds_read_b128 v[232:235], v253 offset:32768
	ds_read_b128 v[236:239], v253 offset:36864
	ds_read_b128 v[240:243], v253 offset:40960
	ds_read_b128 v[244:247], v253 offset:45056
	ds_read_b128 v[228:231], v252 offset:4096
	s_cmp_eq_u32 s2, 0x780
	s_cbranch_scc1 .Lp1_knodma
	v_mfma_f32_32x32x16_bf16 v[114:129], v[150:153], v[170:173], v[114:129]
	s_and_b32 s19, s18, 0x10000
	v_add_u32_e32 v250, s19, v142
	v_lshl_add_u64 v[248:249], v[130:131], 0, s[2:3]
	s_nop 0
	v_readfirstlane_b32 s19, v250
	s_mov_b64 s[22:23], 0x1080
	v_lshl_add_u64 v[250:251], v[248:249], 0, s[22:23]
	s_mov_b32 m0, s19
	s_nop 0
	global_load_lds_dwordx4 v[250:251], off
	v_mfma_f32_32x32x16_bf16 v[82:97], v[150:153], v[174:177], v[82:97]
	s_mov_b64 s[22:23], 0x21080
	v_lshl_add_u64 v[250:251], v[248:249], 0, s[22:23]
	s_add_i32 m0, s19, 0x2000
	s_nop 0
	global_load_lds_dwordx4 v[250:251], off
	v_mfma_f32_32x32x16_bf16 v[98:113], v[150:153], v[178:181], v[98:113]
	s_mov_b64 s[22:23], 0x41080
	v_lshl_add_u64 v[250:251], v[248:249], 0, s[22:23]
	s_add_i32 m0, s19, 0x4000
	s_nop 0
	global_load_lds_dwordx4 v[250:251], off
	v_mfma_f32_32x32x16_bf16 v[66:81], v[150:153], v[182:185], v[66:81]
	s_mov_b64 s[22:23], 0x61080
	v_lshl_add_u64 v[250:251], v[248:249], 0, s[22:23]
	s_add_i32 m0, s19, 0x6000
	s_nop 0
	global_load_lds_dwordx4 v[250:251], off
	v_mfma_f32_32x32x16_bf16 v[50:65], v[166:169], v[170:173], v[50:65]
	v_lshl_add_u64 v[250:251], v[132:133], 0, s[2:3]
	s_add_i32 m0, s19, 0x8000
	s_nop 0
	global_load_lds_dwordx4 v[250:251], off
	v_mfma_f32_32x32x16_bf16 v[18:33], v[166:169], v[174:177], v[18:33]
	v_lshl_add_u64 v[250:251], v[134:135], 0, s[2:3]
	s_add_i32 m0, s19, 0xa000
	s_nop 0
	global_load_lds_dwordx4 v[250:251], off
	v_mfma_f32_32x32x16_bf16 v[34:49], v[166:169], v[178:181], v[34:49]
	v_lshl_add_u64 v[250:251], v[136:137], 0, s[2:3]
	s_add_i32 m0, s19, 0xc000
	s_nop 0
	global_load_lds_dwordx4 v[250:251], off
	v_mfma_f32_32x32x16_bf16 v[2:17], v[166:169], v[182:185], v[2:17]
	v_lshl_add_u64 v[250:251], v[140:141], 0, s[2:3]
	s_add_i32 m0, s19, 0xe000
	s_nop 0
	global_load_lds_dwordx4 v[250:251], off
	s_add_u32 s2, s2, 0x80
	s_addc_u32 s3, s3, 0
	s_add_i32 s18, s18, 0x10000
	s_branch .Lp1_kloop

; #define MFMA(a, b, c) __builtin_amdgcn_mfma_f32_32x32x16_bf16((a), (b), (c), 0, 0, 0)
; #define GEMM_ISSUE(KT, ST) do { const int k1_ = (KT) << 6; unsigned char* d_ = ldst + (ST) * STAGE; \
;         _Pragma("unroll") for (int j_ = 0; j_ < 4; ++j_) dma16(ap + (size_t)(64 * j_) * lda + k1_, d_ + j_ * 8192); \
;         _Pragma("unroll") for (int j_ = 0; j_ < NBW; ++j_) dma16(bp + bro[j_] + k1_, d_ + BOFF + j_ * 8192); } while (0)
; template <int NBW>
; DI void gemm_mainloop(f32x16 (&acc)[2][NBW], const bf16_t* A, size_t lda, int m0, const bf16_t* Bt, size_t ldb, int n0, int K, unsigned char* lds, bool pre = false, bool only_issue = false) {
;     ...
;     for (int kt = 0; kt < nk; ++kt) {
;         const unsigned char* st = lds + (kt & 1) * STAGE;
; #pragma unroll
;         for (int s = 0; s < 4; ++s) {
;             if (s == 1 && kt + 1 < nk) GEMM_ISSUE(kt + 1, (kt + 1) & 1);
;             bf16x8 a[2], b[NBW];
; #pragma unroll
;             for (int mb = 0; mb < 2; ++mb) a[mb] = *(const bf16x8*)(st + aofs + mb * 4096 + xo[s]);
; #pragma unroll
;             for (int nb = 0; nb < NBW; ++nb) b[nb] = *(const bf16x8*)(st + bofs + nb * 4096 + xo[s]);
; #pragma unroll
;             for (int mb = 0; mb < 2; ++mb)
; #pragma unroll
;                 for (int nb = 0; nb < NBW; ++nb) acc[mb][nb] = MFMA(a[mb], b[nb], acc[mb][nb]);
;         }
;         __syncthreads();
.Lp4a_kloop:
	v_add_u32_e32 v65, v63, v58
	v_add_u32_e32 v88, v64, v58
	ds_read_b128 v[224:227], v65
	ds_read_b128 v[232:235], v88 offset:32768
	ds_read_b128 v[236:239], v88 offset:36864
	ds_read_b128 v[228:231], v65 offset:4096
	s_waitcnt lgkmcnt(6)
	v_mfma_f32_32x32x16_bf16 v[66:81], v[240:243], v[248:251], v[66:81]
	s_waitcnt lgkmcnt(5)
	v_mfma_f32_32x32x16_bf16 v[34:49], v[240:243], v[252:255], v[34:49]
	s_waitcnt lgkmcnt(4)
	v_mfma_f32_32x32x16_bf16 v[18:33], v[244:247], v[248:251], v[18:33]
	v_mfma_f32_32x32x16_bf16 v[2:17], v[244:247], v[252:255], v[2:17]
	v_add_u32_e32 v65, v63, v59
	v_add_u32_e32 v88, v64, v59
	ds_read_b128 v[240:243], v65
	ds_read_b128 v[248:251], v88 offset:32768
	ds_read_b128 v[252:255], v88 offset:36864
	ds_read_b128 v[244:247], v65 offset:4096
	s_waitcnt lgkmcnt(6)
	v_mfma_f32_32x32x16_bf16 v[66:81], v[224:227], v[232:235], v[66:81]
	s_waitcnt lgkmcnt(5)
	v_mfma_f32_32x32x16_bf16 v[34:49], v[224:227], v[236:239], v[34:49]
	s_waitcnt lgkmcnt(4)
	v_mfma_f32_32x32x16_bf16 v[18:33], v[228:231], v[232:235], v[18:33]
	v_mfma_f32_32x32x16_bf16 v[2:17], v[228:231], v[236:239], v[2:17]
	v_add_u32_e32 v65, v63, v60
	v_add_u32_e32 v88, v64, v60
	ds_read_b128 v[224:227], v65
	ds_read_b128 v[232:235], v88 offset:32768
	ds_read_b128 v[236:239], v88 offset:36864
	ds_read_b128 v[228:231], v65 offset:4096
	s_waitcnt lgkmcnt(6)
	v_mfma_f32_32x32x16_bf16 v[66:81], v[240:243], v[248:251], v[66:81]
	s_waitcnt lgkmcnt(5)
	v_mfma_f32_32x32x16_bf16 v[34:49], v[240:243], v[252:255], v[34:49]
	s_waitcnt lgkmcnt(4)
	v_mfma_f32_32x32x16_bf16 v[18:33], v[244:247], v[248:251], v[18:33]
	v_mfma_f32_32x32x16_bf16 v[2:17], v[244:247], v[252:255], v[2:17]
	v_xor_b32_e32 v63, 0x10000, v63
	v_xor_b32_e32 v64, 0x10000, v64
	s_waitcnt vmcnt(0) lgkmcnt(0)
	s_barrier
	s_cmp_eq_u32 s76, 0x800
	s_cbranch_scc1 .Lp4a_klast
	v_add_u32_e32 v65, v63, v57
	v_add_u32_e32 v88, v64, v57
	ds_read_b128 v[240:243], v65
	ds_read_b128 v[248:251], v88 offset:32768
	ds_read_b128 v[252:255], v88 offset:36864
	ds_read_b128 v[244:247], v65 offset:4096
	s_cmp_eq_u32 s76, 0x780
	s_cbranch_scc1 .Lp4a_knodma
	v_mfma_f32_32x32x16_bf16 v[66:81], v[224:227], v[232:235], v[66:81]
	s_and_b32 s71, s67, 0x10000
	v_add_u32_e32 v86, s71, v56
	v_lshl_add_u64 v[84:85], v[50:51], 0, s[76:77]
	s_nop 0
	v_readfirstlane_b32 s71, v86
	s_mov_b64 s[86:87], 0xea81080
	v_lshl_add_u64 v[86:87], v[84:85], 0, s[86:87]
	s_mov_b32 m0, s71
	s_nop 0
	global_load_lds_dwordx4 v[86:87], off
	v_mfma_f32_32x32x16_bf16 v[34:49], v[224:227], v[236:239], v[34:49]
	s_mov_b64 s[86:87], 0xeaa1080
	v_lshl_add_u64 v[86:87], v[84:85], 0, s[86:87]
	s_add_i32 m0, s71, 0x2000
	s_nop 0
	global_load_lds_dwordx4 v[86:87], off
	s_mov_b64 s[86:87], 0xeac1080
	v_lshl_add_u64 v[86:87], v[84:85], 0, s[86:87]
	s_add_i32 m0, s71, 0x4000
	s_nop 0
	global_load_lds_dwordx4 v[86:87], off
	v_mfma_f32_32x32x16_bf16 v[18:33], v[228:231], v[232:235], v[18:33]
	s_mov_b64 s[86:87], 0xeae1080
	v_lshl_add_u64 v[86:87], v[84:85], 0, s[86:87]
	s_add_i32 m0, s71, 0x6000
	s_nop 0
	global_load_lds_dwordx4 v[86:87], off
	v_mfma_f32_32x32x16_bf16 v[2:17], v[228:231], v[236:239], v[2:17]
	v_lshl_add_u64 v[86:87], v[52:53], 0, s[76:77]
	s_add_i32 m0, s71, 0x8000
	s_nop 0
	global_load_lds_dwordx4 v[86:87], off
	v_lshl_add_u64 v[86:87], v[54:55], 0, s[76:77]
	s_add_i32 m0, s71, 0xa000
	s_nop 0
	global_load_lds_dwordx4 v[86:87], off
	s_add_u32 s76, s76, 0x80
	s_addc_u32 s77, s77, 0
	s_add_i32 s67, s67, 0x10000
	s_branch .Lp4a_kloop

; #define MFMA(a, b, c) __builtin_amdgcn_mfma_f32_32x32x16_bf16((a), (b), (c), 0, 0, 0)
; #define GEMM_ISSUE(KT, ST) do { const int k1_ = (KT) << 6; unsigned char* d_ = ldst + (ST) * STAGE; \
;         _Pragma("unroll") for (int j_ = 0; j_ < 4; ++j_) dma16(ap + (size_t)(64 * j_) * lda + k1_, d_ + j_ * 8192); \
;         _Pragma("unroll") for (int j_ = 0; j_ < NBW; ++j_) dma16(bp + bro[j_] + k1_, d_ + BOFF + j_ * 8192); } while (0)
; template <int NBW>
; DI void gemm_mainloop(f32x16 (&acc)[2][NBW], const bf16_t* A, size_t lda, int m0, const bf16_t* Bt, size_t ldb, int n0, int K, unsigned char* lds, bool pre = false, bool only_issue = false) {
;     ...
;     for (int kt = 0; kt < nk; ++kt) {
;         const unsigned char* st = lds + (kt & 1) * STAGE;
; #pragma unroll
;         for (int s = 0; s < 4; ++s) {
;             if (s == 1 && kt + 1 < nk) GEMM_ISSUE(kt + 1, (kt + 1) & 1);
;             bf16x8 a[2], b[NBW];
; #pragma unroll
;             for (int mb = 0; mb < 2; ++mb) a[mb] = *(const bf16x8*)(st + aofs + mb * 4096 + xo[s]);
; #pragma unroll
;             for (int nb = 0; nb < NBW; ++nb) b[nb] = *(const bf16x8*)(st + bofs + nb * 4096 + xo[s]);
; #pragma unroll
;             for (int mb = 0; mb < 2; ++mb)
; #pragma unroll
;                 for (int nb = 0; nb < NBW; ++nb) acc[mb][nb] = MFMA(a[mb], b[nb], acc[mb][nb]);
;         }
;         __syncthreads();
.Lp4b_kloop:
	v_add_u32_e32 v157, v134, v145
	v_add_u32_e32 v159, v155, v145
	ds_read_b128 v[224:227], v157
	ds_read_b128 v[232:235], v159 offset:32768
	ds_read_b128 v[236:239], v159 offset:36864
	ds_read_b128 v[228:231], v157 offset:4096
	s_waitcnt lgkmcnt(6)
	v_mfma_f32_32x32x16_bf16 v[114:129], v[240:243], v[248:251], v[114:129]
	s_waitcnt lgkmcnt(5)
	v_mfma_f32_32x32x16_bf16 v[98:113], v[240:243], v[252:255], v[98:113]
	s_waitcnt lgkmcnt(4)
	v_mfma_f32_32x32x16_bf16 v[82:97], v[244:247], v[248:251], v[82:97]
	v_mfma_f32_32x32x16_bf16 v[50:65], v[244:247], v[252:255], v[50:65]
	v_add_u32_e32 v157, v134, v147
	v_add_u32_e32 v159, v155, v147
	ds_read_b128 v[240:243], v157
	ds_read_b128 v[248:251], v159 offset:32768
	ds_read_b128 v[252:255], v159 offset:36864
	ds_read_b128 v[244:247], v157 offset:4096
	s_waitcnt lgkmcnt(6)
	v_mfma_f32_32x32x16_bf16 v[114:129], v[224:227], v[232:235], v[114:129]
	s_waitcnt lgkmcnt(5)
	v_mfma_f32_32x32x16_bf16 v[98:113], v[224:227], v[236:239], v[98:113]
	s_waitcnt lgkmcnt(4)
	v_mfma_f32_32x32x16_bf16 v[82:97], v[228:231], v[232:235], v[82:97]
	v_mfma_f32_32x32x16_bf16 v[50:65], v[228:231], v[236:239], v[50:65]
	v_add_u32_e32 v157, v134, v149
	v_add_u32_e32 v159, v155, v149
	ds_read_b128 v[224:227], v157
	ds_read_b128 v[232:235], v159 offset:32768
	ds_read_b128 v[236:239], v159 offset:36864
	ds_read_b128 v[228:231], v157 offset:4096
	s_waitcnt lgkmcnt(6)
	v_mfma_f32_32x32x16_bf16 v[114:129], v[240:243], v[248:251], v[114:129]
	s_waitcnt lgkmcnt(5)
	v_mfma_f32_32x32x16_bf16 v[98:113], v[240:243], v[252:255], v[98:113]
	s_waitcnt lgkmcnt(4)
	v_mfma_f32_32x32x16_bf16 v[82:97], v[244:247], v[248:251], v[82:97]
	v_mfma_f32_32x32x16_bf16 v[50:65], v[244:247], v[252:255], v[50:65]
	v_xor_b32_e32 v134, 0x10000, v134
	v_xor_b32_e32 v155, 0x10000, v155
	s_waitcnt vmcnt(0) lgkmcnt(0)
	s_barrier
	s_cmp_eq_u32 s72, 0x800
	s_cbranch_scc1 .Lp4b_klast
	v_add_u32_e32 v157, v134, v143
	v_add_u32_e32 v159, v155, v143
	ds_read_b128 v[240:243], v157
	ds_read_b128 v[248:251], v159 offset:32768
	ds_read_b128 v[252:255], v159 offset:36864
	ds_read_b128 v[244:247], v157 offset:4096
	s_cmp_eq_u32 s72, 0x780
	s_cbranch_scc1 .Lp4b_knodma
	v_mfma_f32_32x32x16_bf16 v[114:129], v[224:227], v[232:235], v[114:129]
	s_and_b32 s67, s65, 0x10000
	v_add_u32_e32 v176, s67, v141
	v_lshl_add_u64 v[174:175], v[168:169], 0, s[72:73]
	s_nop 0
	v_readfirstlane_b32 s67, v176
	s_mov_b64 s[76:77], 0x12c01080
	v_lshl_add_u64 v[176:177], v[174:175], 0, s[76:77]
	s_mov_b32 m0, s67
	s_nop 0
	global_load_lds_dwordx4 v[176:177], off
	v_mfma_f32_32x32x16_bf16 v[98:113], v[224:227], v[236:239], v[98:113]
	s_mov_b64 s[76:77], 0x12c21080
	v_lshl_add_u64 v[176:177], v[174:175], 0, s[76:77]
	s_add_i32 m0, s67, 0x2000
	s_nop 0
	global_load_lds_dwordx4 v[176:177], off
	s_mov_b64 s[76:77], 0x12c41080
	v_lshl_add_u64 v[176:177], v[174:175], 0, s[76:77]
	s_add_i32 m0, s67, 0x4000
	s_nop 0
	global_load_lds_dwordx4 v[176:177], off
	v_mfma_f32_32x32x16_bf16 v[82:97], v[228:231], v[232:235], v[82:97]
	s_mov_b64 s[76:77], 0x12c61080
	v_lshl_add_u64 v[176:177], v[174:175], 0, s[76:77]
	s_add_i32 m0, s67, 0x6000
	s_nop 0
	global_load_lds_dwordx4 v[176:177], off
	v_mfma_f32_32x32x16_bf16 v[50:65], v[228:231], v[236:239], v[50:65]
	v_lshl_add_u64 v[176:177], v[170:171], 0, s[72:73]
	s_add_i32 m0, s67, 0x8000
	s_nop 0
	global_load_lds_dwordx4 v[176:177], off
	v_lshl_add_u64 v[176:177], v[172:173], 0, s[72:73]
	s_add_i32 m0, s67, 0xa000
	s_nop 0
	global_load_lds_dwordx4 v[176:177], off
	s_add_u32 s72, s72, 0x80
	s_addc_u32 s73, s73, 0
	s_add_i32 s65, s65, 0x10000
	s_branch .Lp4b_kloop

; #define MFMA(a, b, c) __builtin_amdgcn_mfma_f32_32x32x16_bf16((a), (b), (c), 0, 0, 0)
; #define GEMM_ISSUE(KT, ST) do { const int k1_ = (KT) << 6; unsigned char* d_ = ldst + (ST) * STAGE; \
;         _Pragma("unroll") for (int j_ = 0; j_ < 4; ++j_) dma16(ap + (size_t)(64 * j_) * lda + k1_, d_ + j_ * 8192); \
;         _Pragma("unroll") for (int j_ = 0; j_ < NBW; ++j_) dma16(bp + bro[j_] + k1_, d_ + BOFF + j_ * 8192); } while (0)
; template <int NBW>
; DI void gemm_mainloop(f32x16 (&acc)[2][NBW], const bf16_t* A, size_t lda, int m0, const bf16_t* Bt, size_t ldb, int n0, int K, unsigned char* lds, bool pre = false, bool only_issue = false) {
;     ...
;     for (int kt = 0; kt < nk; ++kt) {
;         const unsigned char* st = lds + (kt & 1) * STAGE;
; #pragma unroll
;         for (int s = 0; s < 4; ++s) {
;             if (s == 1 && kt + 1 < nk) GEMM_ISSUE(kt + 1, (kt + 1) & 1);
;             bf16x8 a[2], b[NBW];
; #pragma unroll
;             for (int mb = 0; mb < 2; ++mb) a[mb] = *(const bf16x8*)(st + aofs + mb * 4096 + xo[s]);
; #pragma unroll
;             for (int nb = 0; nb < NBW; ++nb) b[nb] = *(const bf16x8*)(st + bofs + nb * 4096 + xo[s]);
; #pragma unroll
;             for (int mb = 0; mb < 2; ++mb)
; #pragma unroll
;                 for (int nb = 0; nb < NBW; ++nb) acc[mb][nb] = MFMA(a[mb], b[nb], acc[mb][nb]);
;         }
;         __syncthreads();
.Lp5_kloop:
	v_add_u32_e32 v252, v147, v142
	v_add_u32_e32 v253, v148, v142
	ds_read_b128 v[150:153], v252
	ds_read_b128 v[158:161], v253 offset:32768
	ds_read_b128 v[170:173], v253 offset:36864
	ds_read_b128 v[174:177], v253 offset:40960
	ds_read_b128 v[178:181], v253 offset:45056
	ds_read_b128 v[154:157], v252 offset:4096
	s_waitcnt lgkmcnt(10)
	v_mfma_f32_32x32x16_bf16 v[114:129], v[224:227], v[232:235], v[114:129]
	s_waitcnt lgkmcnt(9)
	v_mfma_f32_32x32x16_bf16 v[98:113], v[224:227], v[236:239], v[98:113]
	s_waitcnt lgkmcnt(8)
	v_mfma_f32_32x32x16_bf16 v[82:97], v[224:227], v[240:243], v[82:97]
	s_waitcnt lgkmcnt(7)
	v_mfma_f32_32x32x16_bf16 v[66:81], v[224:227], v[244:247], v[66:81]
	s_waitcnt lgkmcnt(6)
	v_mfma_f32_32x32x16_bf16 v[50:65], v[228:231], v[232:235], v[50:65]
	v_mfma_f32_32x32x16_bf16 v[34:49], v[228:231], v[236:239], v[34:49]
	v_mfma_f32_32x32x16_bf16 v[18:33], v[228:231], v[240:243], v[18:33]
	v_mfma_f32_32x32x16_bf16 v[2:17], v[228:231], v[244:247], v[2:17]
	v_add_u32_e32 v252, v147, v143
	v_add_u32_e32 v253, v148, v143
	ds_read_b128 v[224:227], v252
	ds_read_b128 v[232:235], v253 offset:32768
	ds_read_b128 v[236:239], v253 offset:36864
	ds_read_b128 v[240:243], v253 offset:40960
	ds_read_b128 v[244:247], v253 offset:45056
	ds_read_b128 v[228:231], v252 offset:4096
	s_waitcnt lgkmcnt(10)
	v_mfma_f32_32x32x16_bf16 v[114:129], v[150:153], v[158:161], v[114:129]
	s_waitcnt lgkmcnt(9)
	v_mfma_f32_32x32x16_bf16 v[98:113], v[150:153], v[170:173], v[98:113]
	s_waitcnt lgkmcnt(8)
	v_mfma_f32_32x32x16_bf16 v[82:97], v[150:153], v[174:177], v[82:97]
	s_waitcnt lgkmcnt(7)
	v_mfma_f32_32x32x16_bf16 v[66:81], v[150:153], v[178:181], v[66:81]
	s_waitcnt lgkmcnt(6)
	v_mfma_f32_32x32x16_bf16 v[50:65], v[154:157], v[158:161], v[50:65]
	v_mfma_f32_32x32x16_bf16 v[34:49], v[154:157], v[170:173], v[34:49]
	v_mfma_f32_32x32x16_bf16 v[18:33], v[154:157], v[174:177], v[18:33]
	v_mfma_f32_32x32x16_bf16 v[2:17], v[154:157], v[178:181], v[2:17]
	v_add_u32_e32 v252, v147, v144
	v_add_u32_e32 v253, v148, v144
	ds_read_b128 v[150:153], v252
	ds_read_b128 v[158:161], v253 offset:32768
	ds_read_b128 v[170:173], v253 offset:36864
	ds_read_b128 v[174:177], v253 offset:40960
	ds_read_b128 v[178:181], v253 offset:45056
	ds_read_b128 v[154:157], v252 offset:4096
	s_waitcnt lgkmcnt(10)
	v_mfma_f32_32x32x16_bf16 v[114:129], v[224:227], v[232:235], v[114:129]
	s_waitcnt lgkmcnt(9)
	v_mfma_f32_32x32x16_bf16 v[98:113], v[224:227], v[236:239], v[98:113]
	s_waitcnt lgkmcnt(8)
	v_mfma_f32_32x32x16_bf16 v[82:97], v[224:227], v[240:243], v[82:97]
	s_waitcnt lgkmcnt(7)
	v_mfma_f32_32x32x16_bf16 v[66:81], v[224:227], v[244:247], v[66:81]
	s_waitcnt lgkmcnt(6)
	v_mfma_f32_32x32x16_bf16 v[50:65], v[228:231], v[232:235], v[50:65]
	v_mfma_f32_32x32x16_bf16 v[34:49], v[228:231], v[236:239], v[34:49]
	v_mfma_f32_32x32x16_bf16 v[18:33], v[228:231], v[240:243], v[18:33]
	v_mfma_f32_32x32x16_bf16 v[2:17], v[228:231], v[244:247], v[2:17]
	v_xor_b32_e32 v147, 0x10000, v147
	v_xor_b32_e32 v148, 0x10000, v148
	s_waitcnt vmcnt(0) lgkmcnt(0)
	s_barrier
	s_cmp_eq_u32 s22, 0x800
	s_cbranch_scc1 .Lp5_klast
	v_add_u32_e32 v252, v147, v141
	v_add_u32_e32 v253, v148, v141
	ds_read_b128 v[224:227], v252
	ds_read_b128 v[232:235], v253 offset:32768
	ds_read_b128 v[236:239], v253 offset:36864
	ds_read_b128 v[240:243], v253 offset:40960
	ds_read_b128 v[244:247], v253 offset:45056
	ds_read_b128 v[228:231], v252 offset:4096
	s_cmp_eq_u32 s22, 0x780
	s_cbranch_scc1 .Lp5_knodma
	v_mfma_f32_32x32x16_bf16 v[114:129], v[150:153], v[158:161], v[114:129]
	s_and_b32 s29, s27, 0x10000
	v_add_u32_e32 v250, s29, v140
	v_lshl_add_u64 v[248:249], v[130:131], 0, s[22:23]
	s_nop 0
	v_readfirstlane_b32 s29, v250
	v_lshl_add_u64 v[250:251], v[248:249], 0, s[14:15]
	s_mov_b32 m0, s29
	s_nop 0
	global_load_lds_dwordx4 v[250:251], off
	v_mfma_f32_32x32x16_bf16 v[98:113], v[150:153], v[170:173], v[98:113]
	v_lshl_add_u64 v[250:251], v[248:249], 0, s[16:17]
	s_add_i32 m0, s29, 0x2000
	s_nop 0
	global_load_lds_dwordx4 v[250:251], off
	v_mfma_f32_32x32x16_bf16 v[82:97], v[150:153], v[174:177], v[82:97]
	v_lshl_add_u64 v[250:251], v[248:249], 0, s[18:19]
	s_add_i32 m0, s29, 0x4000
	s_nop 0
	global_load_lds_dwordx4 v[250:251], off
	v_mfma_f32_32x32x16_bf16 v[66:81], v[150:153], v[178:181], v[66:81]
	v_lshl_add_u64 v[250:251], v[248:249], 0, s[20:21]
	s_add_i32 m0, s29, 0x6000
	s_nop 0
	global_load_lds_dwordx4 v[250:251], off
	v_mfma_f32_32x32x16_bf16 v[50:65], v[154:157], v[158:161], v[50:65]
	v_lshl_add_u64 v[250:251], v[132:133], 0, s[22:23]
	s_add_i32 m0, s29, 0x8000
	s_nop 0
	global_load_lds_dwordx4 v[250:251], off
	v_mfma_f32_32x32x16_bf16 v[34:49], v[154:157], v[170:173], v[34:49]
	v_lshl_add_u64 v[250:251], v[134:135], 0, s[22:23]
	s_add_i32 m0, s29, 0xa000
	s_nop 0
	global_load_lds_dwordx4 v[250:251], off
	v_mfma_f32_32x32x16_bf16 v[18:33], v[154:157], v[174:177], v[18:33]
	v_lshl_add_u64 v[250:251], v[136:137], 0, s[22:23]
	s_add_i32 m0, s29, 0xc000
	s_nop 0
	global_load_lds_dwordx4 v[250:251], off
	v_mfma_f32_32x32x16_bf16 v[2:17], v[154:157], v[178:181], v[2:17]
	v_lshl_add_u64 v[250:251], v[138:139], 0, s[22:23]
	s_add_i32 m0, s29, 0xe000
	s_nop 0
	global_load_lds_dwordx4 v[250:251], off
	s_add_u32 s22, s22, 0x80
	s_addc_u32 s23, s23, 0
	s_add_i32 s27, s27, 0x10000
	s_branch .Lp5_kloop

; #define MFMA(a, b, c) __builtin_amdgcn_mfma_f32_32x32x16_bf16((a), (b), (c), 0, 0, 0)
; #define GEMM_ISSUE(KT, ST) do { const int k1_ = (KT) << 6; unsigned char* d_ = ldst + (ST) * STAGE; \
;         _Pragma("unroll") for (int j_ = 0; j_ < 4; ++j_) dma16(ap + (size_t)(64 * j_) * lda + k1_, d_ + j_ * 8192); \
;         _Pragma("unroll") for (int j_ = 0; j_ < NBW; ++j_) dma16(bp + bro[j_] + k1_, d_ + BOFF + j_ * 8192); } while (0)
; template <int NBW>
; DI void gemm_mainloop(f32x16 (&acc)[2][NBW], const bf16_t* A, size_t lda, int m0, const bf16_t* Bt, size_t ldb, int n0, int K, unsigned char* lds, bool pre = false, bool only_issue = false) {
;     ...
;     for (int kt = 0; kt < nk; ++kt) {
;         const unsigned char* st = lds + (kt & 1) * STAGE;
; #pragma unroll
;         for (int s = 0; s < 4; ++s) {
;             if (s == 1 && kt + 1 < nk) GEMM_ISSUE(kt + 1, (kt + 1) & 1);
;             bf16x8 a[2], b[NBW];
; #pragma unroll
;             for (int mb = 0; mb < 2; ++mb) a[mb] = *(const bf16x8*)(st + aofs + mb * 4096 + xo[s]);
; #pragma unroll
;             for (int nb = 0; nb < NBW; ++nb) b[nb] = *(const bf16x8*)(st + bofs + nb * 4096 + xo[s]);
; #pragma unroll
;             for (int mb = 0; mb < 2; ++mb)
; #pragma unroll
;                 for (int nb = 0; nb < NBW; ++nb) acc[mb][nb] = MFMA(a[mb], b[nb], acc[mb][nb]);
;         }
;         __syncthreads();
.Lp6_kloop:
	v_add_u32_e32 v252, v132, v166
	v_add_u32_e32 v253, v171, v166
	ds_read_b128 v[172:175], v252
	ds_read_b128 v[180:183], v253 offset:32768
	ds_read_b128 v[184:187], v253 offset:36864
	ds_read_b128 v[188:191], v253 offset:40960
	ds_read_b128 v[192:195], v253 offset:45056
	ds_read_b128 v[176:179], v252 offset:4096
	s_waitcnt lgkmcnt(10)
	v_mfma_f32_32x32x16_bf16 v[114:129], v[224:227], v[232:235], v[114:129]
	s_waitcnt lgkmcnt(9)
	v_mfma_f32_32x32x16_bf16 v[98:113], v[224:227], v[236:239], v[98:113]
	s_waitcnt lgkmcnt(8)
	v_mfma_f32_32x32x16_bf16 v[82:97], v[224:227], v[240:243], v[82:97]
	s_waitcnt lgkmcnt(7)
	v_mfma_f32_32x32x16_bf16 v[66:81], v[224:227], v[244:247], v[66:81]
	s_waitcnt lgkmcnt(6)
	v_mfma_f32_32x32x16_bf16 v[50:65], v[228:231], v[232:235], v[50:65]
	v_mfma_f32_32x32x16_bf16 v[34:49], v[228:231], v[236:239], v[34:49]
	v_mfma_f32_32x32x16_bf16 v[18:33], v[228:231], v[240:243], v[18:33]
	v_mfma_f32_32x32x16_bf16 v[2:17], v[228:231], v[244:247], v[2:17]
	v_add_u32_e32 v252, v132, v167
	v_add_u32_e32 v253, v171, v167
	ds_read_b128 v[224:227], v252
	ds_read_b128 v[232:235], v253 offset:32768
	ds_read_b128 v[236:239], v253 offset:36864
	ds_read_b128 v[240:243], v253 offset:40960
	ds_read_b128 v[244:247], v253 offset:45056
	ds_read_b128 v[228:231], v252 offset:4096
	s_waitcnt lgkmcnt(10)
	v_mfma_f32_32x32x16_bf16 v[114:129], v[172:175], v[180:183], v[114:129]
	s_waitcnt lgkmcnt(9)
	v_mfma_f32_32x32x16_bf16 v[98:113], v[172:175], v[184:187], v[98:113]
	s_waitcnt lgkmcnt(8)
	v_mfma_f32_32x32x16_bf16 v[82:97], v[172:175], v[188:191], v[82:97]
	s_waitcnt lgkmcnt(7)
	v_mfma_f32_32x32x16_bf16 v[66:81], v[172:175], v[192:195], v[66:81]
	s_waitcnt lgkmcnt(6)
	v_mfma_f32_32x32x16_bf16 v[50:65], v[176:179], v[180:183], v[50:65]
	v_mfma_f32_32x32x16_bf16 v[34:49], v[176:179], v[184:187], v[34:49]
	v_mfma_f32_32x32x16_bf16 v[18:33], v[176:179], v[188:191], v[18:33]
	v_mfma_f32_32x32x16_bf16 v[2:17], v[176:179], v[192:195], v[2:17]
	v_add_u32_e32 v252, v132, v168
	v_add_u32_e32 v253, v171, v168
	ds_read_b128 v[172:175], v252
	ds_read_b128 v[180:183], v253 offset:32768
	ds_read_b128 v[184:187], v253 offset:36864
	ds_read_b128 v[188:191], v253 offset:40960
	ds_read_b128 v[192:195], v253 offset:45056
	ds_read_b128 v[176:179], v252 offset:4096
	s_waitcnt lgkmcnt(10)
	v_mfma_f32_32x32x16_bf16 v[114:129], v[224:227], v[232:235], v[114:129]
	s_waitcnt lgkmcnt(9)
	v_mfma_f32_32x32x16_bf16 v[98:113], v[224:227], v[236:239], v[98:113]
	s_waitcnt lgkmcnt(8)
	v_mfma_f32_32x32x16_bf16 v[82:97], v[224:227], v[240:243], v[82:97]
	s_waitcnt lgkmcnt(7)
	v_mfma_f32_32x32x16_bf16 v[66:81], v[224:227], v[244:247], v[66:81]
	s_waitcnt lgkmcnt(6)
	v_mfma_f32_32x32x16_bf16 v[50:65], v[228:231], v[232:235], v[50:65]
	v_mfma_f32_32x32x16_bf16 v[34:49], v[228:231], v[236:239], v[34:49]
	v_mfma_f32_32x32x16_bf16 v[18:33], v[228:231], v[240:243], v[18:33]
	v_mfma_f32_32x32x16_bf16 v[2:17], v[228:231], v[244:247], v[2:17]
	v_xor_b32_e32 v132, 0x10000, v132
	v_xor_b32_e32 v171, 0x10000, v171
	s_waitcnt vmcnt(0) lgkmcnt(0)
	s_barrier
	s_cmp_eq_u32 s28, 0x800
	s_cbranch_scc1 .Lp6_klast
	v_add_u32_e32 v252, v132, v165
	v_add_u32_e32 v253, v171, v165
	ds_read_b128 v[224:227], v252
	ds_read_b128 v[232:235], v253 offset:32768
	ds_read_b128 v[236:239], v253 offset:36864
	ds_read_b128 v[240:243], v253 offset:40960
	ds_read_b128 v[244:247], v253 offset:45056
	ds_read_b128 v[228:231], v252 offset:4096
	s_cmp_eq_u32 s28, 0x780
	s_cbranch_scc1 .Lp6_knodma
	v_mfma_f32_32x32x16_bf16 v[114:129], v[172:175], v[180:183], v[114:129]
	s_and_b32 s30, s27, 0x10000
	v_add_u32_e32 v250, s30, v164
	v_lshl_add_u64 v[248:249], v[134:135], 0, s[28:29]
	s_nop 0
	v_readfirstlane_b32 s30, v250
	v_lshl_add_u64 v[250:251], v[248:249], 0, s[16:17]
	s_mov_b32 m0, s30
	s_nop 0
	global_load_lds_dwordx4 v[250:251], off
	v_mfma_f32_32x32x16_bf16 v[98:113], v[172:175], v[184:187], v[98:113]
	v_lshl_add_u64 v[250:251], v[248:249], 0, s[18:19]
	s_add_i32 m0, s30, 0x2000
	s_nop 0
	global_load_lds_dwordx4 v[250:251], off
	v_mfma_f32_32x32x16_bf16 v[82:97], v[172:175], v[188:191], v[82:97]
	v_lshl_add_u64 v[250:251], v[248:249], 0, s[20:21]
	s_add_i32 m0, s30, 0x4000
	s_nop 0
	global_load_lds_dwordx4 v[250:251], off
	v_mfma_f32_32x32x16_bf16 v[66:81], v[172:175], v[192:195], v[66:81]
	v_lshl_add_u64 v[250:251], v[248:249], 0, s[22:23]
	s_add_i32 m0, s30, 0x6000
	s_nop 0
	global_load_lds_dwordx4 v[250:251], off
	v_mfma_f32_32x32x16_bf16 v[50:65], v[176:179], v[180:183], v[50:65]
	v_lshl_add_u64 v[250:251], v[136:137], 0, s[28:29]
	s_add_i32 m0, s30, 0x8000
	s_nop 0
	global_load_lds_dwordx4 v[250:251], off
	v_mfma_f32_32x32x16_bf16 v[34:49], v[176:179], v[184:187], v[34:49]
	v_lshl_add_u64 v[250:251], v[138:139], 0, s[28:29]
	s_add_i32 m0, s30, 0xa000
	s_nop 0
	global_load_lds_dwordx4 v[250:251], off
	v_mfma_f32_32x32x16_bf16 v[18:33], v[176:179], v[188:191], v[18:33]
	v_lshl_add_u64 v[250:251], v[140:141], 0, s[28:29]
	s_add_i32 m0, s30, 0xc000
	s_nop 0
	global_load_lds_dwordx4 v[250:251], off
	v_mfma_f32_32x32x16_bf16 v[2:17], v[176:179], v[192:195], v[2:17]
	v_lshl_add_u64 v[250:251], v[142:143], 0, s[28:29]
	s_add_i32 m0, s30, 0xe000
	s_nop 0
	global_load_lds_dwordx4 v[250:251], off
	s_add_u32 s28, s28, 0x80
	s_addc_u32 s29, s29, 0
	s_add_i32 s27, s27, 0x10000
	s_branch .Lp6_kloop

; #define MFMA(a, b, c) __builtin_amdgcn_mfma_f32_32x32x16_bf16((a), (b), (c), 0, 0, 0)
; #define GEMM_ISSUE(KT, ST) do { const int k1_ = (KT) << 6; unsigned char* d_ = ldst + (ST) * STAGE; \
;         _Pragma("unroll") for (int j_ = 0; j_ < 4; ++j_) dma16(ap + (size_t)(64 * j_) * lda + k1_, d_ + j_ * 8192); \
;         _Pragma("unroll") for (int j_ = 0; j_ < NBW; ++j_) dma16(bp + bro[j_] + k1_, d_ + BOFF + j_ * 8192); } while (0)
; template <int NBW>
; DI void gemm_mainloop(f32x16 (&acc)[2][NBW], const bf16_t* A, size_t lda, int m0, const bf16_t* Bt, size_t ldb, int n0, int K, unsigned char* lds, bool pre = false, bool only_issue = false) {
;     ...
;     for (int kt = 0; kt < nk; ++kt) {
;         const unsigned char* st = lds + (kt & 1) * STAGE;
; #pragma unroll
;         for (int s = 0; s < 4; ++s) {
;             if (s == 1 && kt + 1 < nk) GEMM_ISSUE(kt + 1, (kt + 1) & 1);
;             bf16x8 a[2], b[NBW];
; #pragma unroll
;             for (int mb = 0; mb < 2; ++mb) a[mb] = *(const bf16x8*)(st + aofs + mb * 4096 + xo[s]);
; #pragma unroll
;             for (int nb = 0; nb < NBW; ++nb) b[nb] = *(const bf16x8*)(st + bofs + nb * 4096 + xo[s]);
; #pragma unroll
;             for (int mb = 0; mb < 2; ++mb)
; #pragma unroll
;                 for (int nb = 0; nb < NBW; ++nb) acc[mb][nb] = MFMA(a[mb], b[nb], acc[mb][nb]);
;         }
;         __syncthreads();
.Lp7_kloop:
	v_add_u32_e32 v252, v132, v149
	v_add_u32_e32 v253, v154, v149
	ds_read_b128 v[156:159], v252
	ds_read_b128 v[164:167], v253 offset:32768
	ds_read_b128 v[168:171], v253 offset:36864
	ds_read_b128 v[172:175], v253 offset:40960
	ds_read_b128 v[176:179], v253 offset:45056
	ds_read_b128 v[160:163], v252 offset:4096
	s_waitcnt lgkmcnt(10)
	v_mfma_f32_32x32x16_bf16 v[114:129], v[224:227], v[232:235], v[114:129]
	s_waitcnt lgkmcnt(9)
	v_mfma_f32_32x32x16_bf16 v[98:113], v[224:227], v[236:239], v[98:113]
	s_waitcnt lgkmcnt(8)
	v_mfma_f32_32x32x16_bf16 v[82:97], v[224:227], v[240:243], v[82:97]
	s_waitcnt lgkmcnt(7)
	v_mfma_f32_32x32x16_bf16 v[66:81], v[224:227], v[244:247], v[66:81]
	s_waitcnt lgkmcnt(6)
	v_mfma_f32_32x32x16_bf16 v[50:65], v[228:231], v[232:235], v[50:65]
	v_mfma_f32_32x32x16_bf16 v[34:49], v[228:231], v[236:239], v[34:49]
	v_mfma_f32_32x32x16_bf16 v[18:33], v[228:231], v[240:243], v[18:33]
	v_mfma_f32_32x32x16_bf16 v[2:17], v[228:231], v[244:247], v[2:17]
	v_add_u32_e32 v252, v132, v150
	v_add_u32_e32 v253, v154, v150
	ds_read_b128 v[224:227], v252
	ds_read_b128 v[232:235], v253 offset:32768
	ds_read_b128 v[236:239], v253 offset:36864
	ds_read_b128 v[240:243], v253 offset:40960
	ds_read_b128 v[244:247], v253 offset:45056
	ds_read_b128 v[228:231], v252 offset:4096
	s_waitcnt lgkmcnt(10)
	v_mfma_f32_32x32x16_bf16 v[114:129], v[156:159], v[164:167], v[114:129]
	s_waitcnt lgkmcnt(9)
	v_mfma_f32_32x32x16_bf16 v[98:113], v[156:159], v[168:171], v[98:113]
	s_waitcnt lgkmcnt(8)
	v_mfma_f32_32x32x16_bf16 v[82:97], v[156:159], v[172:175], v[82:97]
	s_waitcnt lgkmcnt(7)
	v_mfma_f32_32x32x16_bf16 v[66:81], v[156:159], v[176:179], v[66:81]
	s_waitcnt lgkmcnt(6)
	v_mfma_f32_32x32x16_bf16 v[50:65], v[160:163], v[164:167], v[50:65]
	v_mfma_f32_32x32x16_bf16 v[34:49], v[160:163], v[168:171], v[34:49]
	v_mfma_f32_32x32x16_bf16 v[18:33], v[160:163], v[172:175], v[18:33]
	v_mfma_f32_32x32x16_bf16 v[2:17], v[160:163], v[176:179], v[2:17]
	v_add_u32_e32 v252, v132, v151
	v_add_u32_e32 v253, v154, v151
	ds_read_b128 v[156:159], v252
	ds_read_b128 v[164:167], v253 offset:32768
	ds_read_b128 v[168:171], v253 offset:36864
	ds_read_b128 v[172:175], v253 offset:40960
	ds_read_b128 v[176:179], v253 offset:45056
	ds_read_b128 v[160:163], v252 offset:4096
	s_waitcnt lgkmcnt(10)
	v_mfma_f32_32x32x16_bf16 v[114:129], v[224:227], v[232:235], v[114:129]
	s_waitcnt lgkmcnt(9)
	v_mfma_f32_32x32x16_bf16 v[98:113], v[224:227], v[236:239], v[98:113]
	s_waitcnt lgkmcnt(8)
	v_mfma_f32_32x32x16_bf16 v[82:97], v[224:227], v[240:243], v[82:97]
	s_waitcnt lgkmcnt(7)
	v_mfma_f32_32x32x16_bf16 v[66:81], v[224:227], v[244:247], v[66:81]
	s_waitcnt lgkmcnt(6)
	v_mfma_f32_32x32x16_bf16 v[50:65], v[228:231], v[232:235], v[50:65]
	v_mfma_f32_32x32x16_bf16 v[34:49], v[228:231], v[236:239], v[34:49]
	v_mfma_f32_32x32x16_bf16 v[18:33], v[228:231], v[240:243], v[18:33]
	v_mfma_f32_32x32x16_bf16 v[2:17], v[228:231], v[244:247], v[2:17]
	v_xor_b32_e32 v132, 0x10000, v132
	v_xor_b32_e32 v154, 0x10000, v154
	s_waitcnt vmcnt(0) lgkmcnt(0)
	s_barrier
	s_cmp_eq_u32 s22, 0x2000
	s_cbranch_scc1 .Lp7_klast
	v_add_u32_e32 v252, v132, v148
	v_add_u32_e32 v253, v154, v148
	ds_read_b128 v[224:227], v252
	ds_read_b128 v[232:235], v253 offset:32768
	ds_read_b128 v[236:239], v253 offset:36864
	ds_read_b128 v[240:243], v253 offset:40960
	ds_read_b128 v[244:247], v253 offset:45056
	ds_read_b128 v[228:231], v252 offset:4096
	s_cmp_eq_u32 s22, 0x1f80
	s_cbranch_scc1 .Lp7_knodma
	v_mfma_f32_32x32x16_bf16 v[114:129], v[156:159], v[164:167], v[114:129]
	s_and_b32 s24, s21, 0x10000
	v_add_u32_e32 v250, s24, v147
	v_lshl_add_u64 v[248:249], v[134:135], 0, s[22:23]
	s_nop 0
	v_readfirstlane_b32 s24, v250
	v_lshl_add_u64 v[250:251], v[248:249], 0, s[10:11]
	s_mov_b32 m0, s24
	s_nop 0
	global_load_lds_dwordx4 v[250:251], off
	v_mfma_f32_32x32x16_bf16 v[98:113], v[156:159], v[168:171], v[98:113]
	v_lshl_add_u64 v[250:251], v[248:249], 0, s[12:13]
	s_add_i32 m0, s24, 0x2000
	s_nop 0
	global_load_lds_dwordx4 v[250:251], off
	v_mfma_f32_32x32x16_bf16 v[82:97], v[156:159], v[172:175], v[82:97]
	v_lshl_add_u64 v[250:251], v[248:249], 0, s[14:15]
	s_add_i32 m0, s24, 0x4000
	s_nop 0
	global_load_lds_dwordx4 v[250:251], off
	v_mfma_f32_32x32x16_bf16 v[66:81], v[156:159], v[176:179], v[66:81]
	v_lshl_add_u64 v[250:251], v[248:249], 0, s[16:17]
	s_add_i32 m0, s24, 0x6000
	s_nop 0
	global_load_lds_dwordx4 v[250:251], off
	v_mfma_f32_32x32x16_bf16 v[50:65], v[160:163], v[164:167], v[50:65]
	v_lshl_add_u64 v[250:251], v[136:137], 0, s[22:23]
	s_add_i32 m0, s24, 0x8000
	s_nop 0
	global_load_lds_dwordx4 v[250:251], off
	v_mfma_f32_32x32x16_bf16 v[34:49], v[160:163], v[168:171], v[34:49]
	v_lshl_add_u64 v[250:251], v[138:139], 0, s[22:23]
	s_add_i32 m0, s24, 0xa000
	s_nop 0
	global_load_lds_dwordx4 v[250:251], off
	v_mfma_f32_32x32x16_bf16 v[18:33], v[160:163], v[172:175], v[18:33]
	v_lshl_add_u64 v[250:251], v[140:141], 0, s[22:23]
	s_add_i32 m0, s24, 0xc000
	s_nop 0
	global_load_lds_dwordx4 v[250:251], off
	v_mfma_f32_32x32x16_bf16 v[2:17], v[160:163], v[176:179], v[2:17]
	v_lshl_add_u64 v[250:251], v[142:143], 0, s[22:23]
	s_add_i32 m0, s24, 0xe000
	s_nop 0
	global_load_lds_dwordx4 v[250:251], off
	s_add_u32 s22, s22, 0x80
	s_addc_u32 s23, s23, 0
	s_add_i32 s21, s21, 0x10000
	s_branch .Lp7_kloop
